# grid barrier: arrivers 0 and 16 of each XCC issue an early un-waited L2 write-back (release protocol unchanged)
# speedup vs baseline: 1.0149x; 1.0149x over previous
; __device__ __forceinline__ void grid_barrier(unsigned* bar, unsigned k, unsigned info, int swave) {
;     ...
;       const unsigned old = __hip_atomic_fetch_add(bar + 64 * (8 + myxcc), 1u, __ATOMIC_RELAXED, __HIP_MEMORY_SCOPE_AGENT);
;       if (old + 1u == k * nmine) {
;         __builtin_amdgcn_fence(__ATOMIC_RELEASE, "agent");
;         asm volatile("s_waitcnt vmcnt(0)" ::: "memory");
;         __hip_atomic_fetch_add(bar + 64 * 16, 1u, __ATOMIC_RELAXED, __HIP_MEMORY_SCOPE_AGENT);
;       }
.LBB0_30:
	s_or_b64 exec, exec, s[2:3]
	s_waitcnt vmcnt(0)
	v_readfirstlane_b32 s2, v1
	v_readlane_b32 s3, v247, 43
	s_nop 0
	v_add3_u32 v0, s2, v0, 1
	v_readlane_b32 s2, v248, 60
	s_mul_i32 s2, s3, s2
	s_nop 0
	v_readlane_b32 s4, v248, 60
	s_sub_i32 s4, s2, s4
	s_add_i32 s4, s4, 1
	v_subrev_u32_e32 v1, s4, v0
	v_and_b32_e32 v1, 15, v1
	v_cmp_eq_u32_e32 vcc, 0, v1
	s_cbranch_vccz .Lxb_noflush
	buffer_wbl2 sc1
.Lxb_noflush:
	v_cmp_eq_u32_e32 vcc, s2, v0
	s_and_saveexec_b64 s[2:3], vcc
	s_cbranch_execz .LBB0_33
	s_mov_b64 s[4:5], exec
	v_mbcnt_lo_u32_b32 v0, s4, 0
	buffer_wbl2 sc1
	s_waitcnt vmcnt(0)
	v_mbcnt_hi_u32_b32 v0, s5, v0
	v_cmp_eq_u32_e32 vcc, 0, v0
	s_and_b64 s[6:7], exec, vcc
	s_mov_b64 exec, s[6:7]
	s_cbranch_execz .LBB0_33
	s_bcnt1_i32_b64 s4, s[4:5]
	v_mov_b32_e32 v0, s4
	global_atomic_add v3, v0, s[86:87]
